# bias-fold FFN-F2 epilogue shifted 16 bytes relative to its loop (placement)
# baseline (speedup 1.0000x reference)
.LBB0_1057:
	s_add_u32 s12, s0, 0xfff80080
	s_addc_u32 s13, s1, -1
	s_add_i32 s50, 0, 0x10000
	s_cmp_eq_u32 s33, 28
	s_cselect_b32 s15, s20, s13
	s_cselect_b32 s14, s21, s12
	s_cselect_b32 s13, s22, s27
	s_cselect_b32 s12, s23, s26
	s_add_i32 s53, 0, 0x14000
	ds_read_b128 v[88:91], v253
	ds_read_b128 v[92:95], v253 offset:1024
	ds_read_b128 v[96:99], v253 offset:2048
	ds_read_b128 v[100:103], v253 offset:3072
	ds_read_b128 v[108:111], v253 offset:16384
	ds_read_b128 v[112:115], v253 offset:17408
	ds_read_b128 v[116:119], v253 offset:18432
	ds_read_b128 v[120:123], v253 offset:19456
	s_add_i32 m0, s42, 0xc000
	ds_read_b128 v[152:155], v224
	ds_read_b128 v[164:167], v224 offset:1024
	ds_read_b128 v[168:171], v224 offset:2048
	ds_read_b128 v[172:175], v224 offset:3072
	ds_read_b128 v[188:191], v224 offset:4096
	ds_read_b128 v[192:195], v224 offset:5120
	ds_read_b128 v[196:199], v224 offset:6144
	ds_read_b128 v[200:203], v224 offset:7168
	global_load_lds_dwordx4 v184, s[0:1]
	s_add_i32 m0, s42, 0xe000
	s_nop 0
	global_load_lds_dwordx4 v186, s[0:1]
	s_waitcnt vmcnt(8)
	s_waitcnt lgkmcnt(0)
	s_barrier
	s_setprio 1
	s_waitcnt lgkmcnt(0)
	v_mfma_f32_16x16x32_bf16 v[160:163], v[88:91], v[152:155], v[160:163]
	v_mfma_f32_16x16x32_bf16 v[156:159], v[96:99], v[152:155], v[156:159]
	v_mfma_f32_16x16x32_bf16 v[148:151], v[88:91], v[168:171], v[148:151]
	v_mfma_f32_16x16x32_bf16 v[144:147], v[96:99], v[168:171], v[144:147]
	v_mfma_f32_16x16x32_bf16 v[140:143], v[88:91], v[188:191], v[140:143]
	v_mfma_f32_16x16x32_bf16 v[136:139], v[96:99], v[188:191], v[136:139]
	v_mfma_f32_16x16x32_bf16 v[132:135], v[88:91], v[196:199], v[132:135]
	v_mfma_f32_16x16x32_bf16 v[128:131], v[96:99], v[196:199], v[128:131]
	v_mfma_f32_16x16x32_bf16 v[160:163], v[92:95], v[164:167], v[160:163]
	v_mfma_f32_16x16x32_bf16 v[156:159], v[100:103], v[164:167], v[156:159]
	v_mfma_f32_16x16x32_bf16 v[148:151], v[92:95], v[172:175], v[148:151]
	v_mfma_f32_16x16x32_bf16 v[144:147], v[100:103], v[172:175], v[144:147]
	v_mfma_f32_16x16x32_bf16 v[140:143], v[92:95], v[192:195], v[140:143]
	v_mfma_f32_16x16x32_bf16 v[136:139], v[100:103], v[192:195], v[136:139]
	v_mfma_f32_16x16x32_bf16 v[132:135], v[92:95], v[200:203], v[132:135]
	v_mfma_f32_16x16x32_bf16 v[128:131], v[100:103], v[200:203], v[128:131]
	s_setprio 0
	s_setprio 1
	v_mfma_f32_16x16x32_bf16 v[60:63], v[108:111], v[152:155], v[60:63]
	v_mfma_f32_16x16x32_bf16 v[56:59], v[116:119], v[152:155], v[56:59]
	v_mfma_f32_16x16x32_bf16 v[52:55], v[108:111], v[168:171], v[52:55]
	v_mfma_f32_16x16x32_bf16 v[48:51], v[116:119], v[168:171], v[48:51]
	v_mfma_f32_16x16x32_bf16 v[44:47], v[108:111], v[188:191], v[44:47]
	v_mfma_f32_16x16x32_bf16 v[40:43], v[116:119], v[188:191], v[40:43]
	v_mfma_f32_16x16x32_bf16 v[36:39], v[108:111], v[196:199], v[36:39]
	v_mfma_f32_16x16x32_bf16 v[32:35], v[116:119], v[196:199], v[32:35]
	v_mfma_f32_16x16x32_bf16 v[60:63], v[112:115], v[164:167], v[60:63]
	v_mfma_f32_16x16x32_bf16 v[56:59], v[120:123], v[164:167], v[56:59]
	v_mfma_f32_16x16x32_bf16 v[52:55], v[112:115], v[172:175], v[52:55]
	v_mfma_f32_16x16x32_bf16 v[48:51], v[120:123], v[172:175], v[48:51]
	v_mfma_f32_16x16x32_bf16 v[44:47], v[112:115], v[192:195], v[44:47]
	v_mfma_f32_16x16x32_bf16 v[40:43], v[120:123], v[192:195], v[40:43]
	v_mfma_f32_16x16x32_bf16 v[36:39], v[112:115], v[200:203], v[36:39]
	v_mfma_f32_16x16x32_bf16 v[32:35], v[120:123], v[200:203], v[32:35]
	s_setprio 0
	s_barrier
	s_add_i32 s50, s50, s39
	s_mov_b32 m0, s50
	ds_read_b128 v[152:155], v224 offset:16384
	ds_read_b128 v[164:167], v224 offset:17408
	ds_read_b128 v[168:171], v224 offset:18432
	ds_read_b128 v[172:175], v224 offset:19456
	ds_read_b128 v[188:191], v224 offset:20480
	ds_read_b128 v[192:195], v224 offset:21504
	ds_read_b128 v[196:199], v224 offset:22528
	ds_read_b128 v[200:203], v224 offset:23552
	global_load_lds_dwordx4 v176, s[12:13]
	s_add_i32 m0, s50, 0x2000
	s_add_u32 s50, s12, 0x80000
	s_addc_u32 s51, s13, 0
	s_add_i32 s53, s53, s39
	global_load_lds_dwordx4 v178, s[12:13]
	s_mov_b32 m0, s53
	s_nop 0
	global_load_lds_dwordx4 v176, s[50:51]
	s_add_i32 m0, s53, 0x2000
	s_nop 0
	global_load_lds_dwordx4 v178, s[50:51]
	s_add_u32 s62, s14, 0x80
	s_addc_u32 s63, s15, 0
	s_mov_b32 m0, s42
	s_nop 0
	global_load_lds_dwordx4 v182, s[14:15]
	s_mov_b32 m0, s43
	s_nop 0
	global_load_lds_dwordx4 v180, s[14:15]
	s_waitcnt vmcnt(8)
	s_waitcnt lgkmcnt(0)
	s_barrier
	s_setprio 1
	s_waitcnt lgkmcnt(0)
	v_mfma_f32_16x16x32_bf16 v[124:127], v[88:91], v[152:155], v[124:127]
	v_mfma_f32_16x16x32_bf16 v[104:107], v[96:99], v[152:155], v[104:107]
	v_mfma_f32_16x16x32_bf16 v[84:87], v[88:91], v[168:171], v[84:87]
	v_mfma_f32_16x16x32_bf16 v[80:83], v[96:99], v[168:171], v[80:83]
	v_mfma_f32_16x16x32_bf16 v[76:79], v[88:91], v[188:191], v[76:79]
	v_mfma_f32_16x16x32_bf16 v[72:75], v[96:99], v[188:191], v[72:75]
	v_mfma_f32_16x16x32_bf16 v[68:71], v[88:91], v[196:199], v[68:71]
	v_mfma_f32_16x16x32_bf16 v[64:67], v[96:99], v[196:199], v[64:67]
	v_mfma_f32_16x16x32_bf16 v[124:127], v[92:95], v[164:167], v[124:127]
	v_mfma_f32_16x16x32_bf16 v[104:107], v[100:103], v[164:167], v[104:107]
	v_mfma_f32_16x16x32_bf16 v[84:87], v[92:95], v[172:175], v[84:87]
	v_mfma_f32_16x16x32_bf16 v[80:83], v[100:103], v[172:175], v[80:83]
	v_mfma_f32_16x16x32_bf16 v[76:79], v[92:95], v[192:195], v[76:79]
	v_mfma_f32_16x16x32_bf16 v[72:75], v[100:103], v[192:195], v[72:75]
	v_mfma_f32_16x16x32_bf16 v[68:71], v[92:95], v[200:203], v[68:71]
	v_mfma_f32_16x16x32_bf16 v[64:67], v[100:103], v[200:203], v[64:67]
	s_setprio 0
	s_setprio 1
	v_mfma_f32_16x16x32_bf16 v[28:31], v[108:111], v[152:155], v[28:31]
	v_mfma_f32_16x16x32_bf16 v[24:27], v[116:119], v[152:155], v[24:27]
	v_mfma_f32_16x16x32_bf16 v[20:23], v[108:111], v[168:171], v[20:23]
	v_mfma_f32_16x16x32_bf16 v[16:19], v[116:119], v[168:171], v[16:19]
	v_mfma_f32_16x16x32_bf16 v[12:15], v[108:111], v[188:191], v[12:15]
	v_mfma_f32_16x16x32_bf16 v[8:11], v[116:119], v[188:191], v[8:11]
	v_mfma_f32_16x16x32_bf16 v[4:7], v[108:111], v[196:199], v[4:7]
	v_mfma_f32_16x16x32_bf16 v[0:3], v[116:119], v[196:199], v[0:3]
	v_mfma_f32_16x16x32_bf16 v[28:31], v[112:115], v[164:167], v[28:31]
	v_mfma_f32_16x16x32_bf16 v[24:27], v[120:123], v[164:167], v[24:27]
	v_mfma_f32_16x16x32_bf16 v[20:23], v[112:115], v[172:175], v[20:23]
	v_mfma_f32_16x16x32_bf16 v[16:19], v[120:123], v[172:175], v[16:19]
	v_mfma_f32_16x16x32_bf16 v[12:15], v[112:115], v[192:195], v[12:15]
	v_mfma_f32_16x16x32_bf16 v[8:11], v[120:123], v[192:195], v[8:11]
	v_mfma_f32_16x16x32_bf16 v[4:7], v[112:115], v[200:203], v[4:7]
	v_mfma_f32_16x16x32_bf16 v[0:3], v[120:123], v[200:203], v[0:3]
	s_setprio 0
	s_barrier
	s_add_i32 s50, 0, 0x18000
	s_add_i32 s51, 0, 0x1c000
	ds_read_b128 v[88:91], v253 offset:32768
	ds_read_b128 v[92:95], v253 offset:33792
	ds_read_b128 v[96:99], v253 offset:34816
	ds_read_b128 v[100:103], v253 offset:35840
	ds_read_b128 v[108:111], v253 offset:49152
	ds_read_b128 v[112:115], v253 offset:50176
	ds_read_b128 v[116:119], v253 offset:51200
	ds_read_b128 v[120:123], v253 offset:52224
	s_add_u32 s14, s14, 0x80000
	s_addc_u32 s15, s15, 0
	s_mov_b32 m0, s44
	ds_read_b128 v[152:155], v224 offset:32768
	ds_read_b128 v[164:167], v224 offset:33792
	ds_read_b128 v[168:171], v224 offset:34816
	ds_read_b128 v[172:175], v224 offset:35840
	ds_read_b128 v[188:191], v224 offset:36864
	ds_read_b128 v[192:195], v224 offset:37888
	ds_read_b128 v[196:199], v224 offset:38912
	ds_read_b128 v[200:203], v224 offset:39936
	global_load_lds_dwordx4 v182, s[14:15]
	s_mov_b32 m0, s45
	s_nop 0
	global_load_lds_dwordx4 v180, s[14:15]
	s_waitcnt vmcnt(8)
	s_waitcnt lgkmcnt(0)
	s_barrier
	s_setprio 1
	s_waitcnt lgkmcnt(0)
	v_mfma_f32_16x16x32_bf16 v[160:163], v[88:91], v[152:155], v[160:163]
	v_mfma_f32_16x16x32_bf16 v[156:159], v[96:99], v[152:155], v[156:159]
	v_mfma_f32_16x16x32_bf16 v[148:151], v[88:91], v[168:171], v[148:151]
	v_mfma_f32_16x16x32_bf16 v[144:147], v[96:99], v[168:171], v[144:147]
	v_mfma_f32_16x16x32_bf16 v[140:143], v[88:91], v[188:191], v[140:143]
	v_mfma_f32_16x16x32_bf16 v[136:139], v[96:99], v[188:191], v[136:139]
	v_mfma_f32_16x16x32_bf16 v[132:135], v[88:91], v[196:199], v[132:135]
	v_mfma_f32_16x16x32_bf16 v[128:131], v[96:99], v[196:199], v[128:131]
	v_mfma_f32_16x16x32_bf16 v[160:163], v[92:95], v[164:167], v[160:163]
	v_mfma_f32_16x16x32_bf16 v[156:159], v[100:103], v[164:167], v[156:159]
	v_mfma_f32_16x16x32_bf16 v[148:151], v[92:95], v[172:175], v[148:151]
	v_mfma_f32_16x16x32_bf16 v[144:147], v[100:103], v[172:175], v[144:147]
	v_mfma_f32_16x16x32_bf16 v[140:143], v[92:95], v[192:195], v[140:143]
	v_mfma_f32_16x16x32_bf16 v[136:139], v[100:103], v[192:195], v[136:139]
	v_mfma_f32_16x16x32_bf16 v[132:135], v[92:95], v[200:203], v[132:135]
	v_mfma_f32_16x16x32_bf16 v[128:131], v[100:103], v[200:203], v[128:131]
	s_setprio 0
	s_setprio 1
	v_mfma_f32_16x16x32_bf16 v[60:63], v[108:111], v[152:155], v[60:63]
	v_mfma_f32_16x16x32_bf16 v[56:59], v[116:119], v[152:155], v[56:59]
	v_mfma_f32_16x16x32_bf16 v[52:55], v[108:111], v[168:171], v[52:55]
	v_mfma_f32_16x16x32_bf16 v[48:51], v[116:119], v[168:171], v[48:51]
	v_mfma_f32_16x16x32_bf16 v[44:47], v[108:111], v[188:191], v[44:47]
	v_mfma_f32_16x16x32_bf16 v[40:43], v[116:119], v[188:191], v[40:43]
	v_mfma_f32_16x16x32_bf16 v[36:39], v[108:111], v[196:199], v[36:39]
	v_mfma_f32_16x16x32_bf16 v[32:35], v[116:119], v[196:199], v[32:35]
	v_mfma_f32_16x16x32_bf16 v[60:63], v[112:115], v[164:167], v[60:63]
	v_mfma_f32_16x16x32_bf16 v[56:59], v[120:123], v[164:167], v[56:59]
	v_mfma_f32_16x16x32_bf16 v[52:55], v[112:115], v[172:175], v[52:55]
	v_mfma_f32_16x16x32_bf16 v[48:51], v[120:123], v[172:175], v[48:51]
	v_mfma_f32_16x16x32_bf16 v[44:47], v[112:115], v[192:195], v[44:47]
	v_mfma_f32_16x16x32_bf16 v[40:43], v[120:123], v[192:195], v[40:43]
	v_mfma_f32_16x16x32_bf16 v[36:39], v[112:115], v[200:203], v[36:39]
	v_mfma_f32_16x16x32_bf16 v[32:35], v[120:123], v[200:203], v[32:35]
	s_setprio 0
	s_barrier
	s_add_i32 s14, s50, s39
	s_mov_b32 m0, s14
	ds_read_b128 v[152:155], v224 offset:49152
	ds_read_b128 v[164:167], v224 offset:50176
	ds_read_b128 v[168:171], v224 offset:51200
	ds_read_b128 v[172:175], v224 offset:52224
	ds_read_b128 v[188:191], v224 offset:53248
	ds_read_b128 v[192:195], v224 offset:54272
	ds_read_b128 v[196:199], v224 offset:55296
	ds_read_b128 v[200:203], v224 offset:56320
	s_add_u32 s98, s12, 0x80
	s_addc_u32 s99, s13, 0
	global_load_lds_dwordx4 v176, s[98:99]
	s_add_i32 m0, s14, 0x2000
	s_add_u32 s12, s12, 0x80080
	s_addc_u32 s13, s13, 0
	s_add_i32 s14, s51, s39
	s_add_u32 s98, s12, 0xfff80000
	s_addc_u32 s99, s13, -1
	global_load_lds_dwordx4 v178, s[98:99]
	s_mov_b32 m0, s14
	s_nop 0
	global_load_lds_dwordx4 v176, s[12:13]
	s_add_i32 m0, s14, 0x2000
	s_nop 0
	global_load_lds_dwordx4 v178, s[12:13]
	s_mov_b32 m0, s61
	s_nop 0
	global_load_lds_dwordx4 v182, s[62:63]
	s_mov_b32 m0, s64
	s_nop 0
	global_load_lds_dwordx4 v180, s[62:63]
	s_waitcnt vmcnt(8)
	s_waitcnt lgkmcnt(0)
	s_barrier
	s_setprio 1
	s_waitcnt lgkmcnt(0)
	v_mfma_f32_16x16x32_bf16 v[124:127], v[88:91], v[152:155], v[124:127]
	v_mfma_f32_16x16x32_bf16 v[104:107], v[96:99], v[152:155], v[104:107]
	v_mfma_f32_16x16x32_bf16 v[84:87], v[88:91], v[168:171], v[84:87]
	v_mfma_f32_16x16x32_bf16 v[80:83], v[96:99], v[168:171], v[80:83]
	v_mfma_f32_16x16x32_bf16 v[76:79], v[88:91], v[188:191], v[76:79]
	v_mfma_f32_16x16x32_bf16 v[72:75], v[96:99], v[188:191], v[72:75]
	v_mfma_f32_16x16x32_bf16 v[68:71], v[88:91], v[196:199], v[68:71]
	v_mfma_f32_16x16x32_bf16 v[64:67], v[96:99], v[196:199], v[64:67]
	v_mfma_f32_16x16x32_bf16 v[124:127], v[92:95], v[164:167], v[124:127]
	v_mfma_f32_16x16x32_bf16 v[104:107], v[100:103], v[164:167], v[104:107]
	v_mfma_f32_16x16x32_bf16 v[84:87], v[92:95], v[172:175], v[84:87]
	v_mfma_f32_16x16x32_bf16 v[80:83], v[100:103], v[172:175], v[80:83]
	v_mfma_f32_16x16x32_bf16 v[76:79], v[92:95], v[192:195], v[76:79]
	v_mfma_f32_16x16x32_bf16 v[72:75], v[100:103], v[192:195], v[72:75]
	v_mfma_f32_16x16x32_bf16 v[68:71], v[92:95], v[200:203], v[68:71]
	v_mfma_f32_16x16x32_bf16 v[64:67], v[100:103], v[200:203], v[64:67]
	s_setprio 0
	s_setprio 1
	v_mfma_f32_16x16x32_bf16 v[28:31], v[108:111], v[152:155], v[28:31]
	v_mfma_f32_16x16x32_bf16 v[24:27], v[116:119], v[152:155], v[24:27]
	v_mfma_f32_16x16x32_bf16 v[20:23], v[108:111], v[168:171], v[20:23]
	v_mfma_f32_16x16x32_bf16 v[16:19], v[116:119], v[168:171], v[16:19]
	v_mfma_f32_16x16x32_bf16 v[12:15], v[108:111], v[188:191], v[12:15]
	v_mfma_f32_16x16x32_bf16 v[8:11], v[116:119], v[188:191], v[8:11]
	v_mfma_f32_16x16x32_bf16 v[4:7], v[108:111], v[196:199], v[4:7]
	v_mfma_f32_16x16x32_bf16 v[0:3], v[116:119], v[196:199], v[0:3]
	v_mfma_f32_16x16x32_bf16 v[28:31], v[112:115], v[164:167], v[28:31]
	v_mfma_f32_16x16x32_bf16 v[24:27], v[120:123], v[164:167], v[24:27]
	v_mfma_f32_16x16x32_bf16 v[20:23], v[112:115], v[172:175], v[20:23]
	v_mfma_f32_16x16x32_bf16 v[16:19], v[120:123], v[172:175], v[16:19]
	v_mfma_f32_16x16x32_bf16 v[12:15], v[112:115], v[192:195], v[12:15]
	v_mfma_f32_16x16x32_bf16 v[8:11], v[120:123], v[192:195], v[8:11]
	v_mfma_f32_16x16x32_bf16 v[4:7], v[112:115], v[200:203], v[4:7]
	v_mfma_f32_16x16x32_bf16 v[0:3], v[120:123], v[200:203], v[0:3]
	s_setprio 0
	s_barrier
	s_add_i32 s33, s33, 2
	s_add_u32 s0, s0, 0x100
	s_addc_u32 s1, s1, 0
	s_add_u32 s26, s26, 0x100
	s_addc_u32 s27, s27, 0
	s_cmp_gt_u32 s33, 29
	s_cbranch_scc0 .LBB0_1057
	s_nop 0
	s_nop 0
	s_nop 0
	s_nop 0
	s_and_b64 vcc, exec, s[40:41]
	s_cbranch_vccz .LBB0_1060
	s_barrier
